# v10: + sample HGRN2 recurrence on all 8 waves (k split 4 ways, loads up front, partial dot products summed through LDS); selection/window K,V prep: V gathers issued with the K row loads
# speedup vs baseline: 1.0280x; 1.0058x over previous
.LBB0_929:
	s_cmp_lt_i32 s96, 5
	s_cselect_b64 s[42:43], -1, 0
	s_and_b64 s[0:1], s[42:43], s[0:1]
	s_andn2_b64 vcc, exec, s[0:1]
	s_cbranch_vccnz .LBB0_972
	s_add_u32 s46, s90, 0x48591600
	s_addc_u32 s47, s91, 0
	s_add_u32 s48, s90, 0xae1b600
	s_addc_u32 s49, s91, 0
	s_and_b32 s0, s87, 0xffffffc0
	v_mbcnt_hi_u32_b32 v135, -1, v216
	v_add_u32_e32 v64, s0, v135
	s_and_b32 s6, s94, -8
	s_movk_i32 s0, 0x80
	s_mov_b32 s3, 0
	s_and_b32 s8, s94, 7
	s_ashr_i32 s7, s6, 31
	v_cmp_gt_i32_e32 vcc, s0, v64
	v_ashrrev_i32_e32 v65, 31, v64
	v_lshrrev_b32_e32 v98, 6, v64
	v_and_b32_e32 v99, 63, v64
	s_mul_i32 s2, s6, 0x1100
	s_lshl_b32 s3, s8, 9
	s_add_u32 s2, s2, s3
	v_mul_u32_u24_e32 v100, 0x1100, v98
	v_lshl_add_u32 v100, v99, 3, v100
	v_add_u32_e32 v100, s2, v100
	s_add_u32 s10, s90, 0xd01b600
	s_addc_u32 s11, s91, 0
	global_load_dwordx2 v[102:103], v100, s[10:11]
	s_mul_i32 s4, s6, 0x880
	s_lshl_b32 s5, s8, 8
	s_add_u32 s4, s4, s5
	v_mul_u32_u24_e32 v101, 0x880, v98
	v_lshl_add_u32 v101, v99, 2, v101
	v_add_u32_e32 v101, s4, v101
	s_add_u32 s12, s90, 0x49691600
	s_addc_u32 s13, s91, 0
	global_load_dword v104, v101, s[12:13]
	v_readlane_b32 s26, v239, 17
	v_readlane_b32 s27, v239, 18
	v_and_b32_e32 v129, 0x7f, v64
	v_lshrrev_b32_e32 v122, 7, v64
	v_lshlrev_b32_e32 v123, 14, v122
	v_lshl_add_u32 v123, v129, 2, v123
	s_lshl_b32 s14, s94, 16
	s_add_u32 s16, s26, s14
	s_addc_u32 s17, s27, 0
	global_load_dword v0, v123, s[16:17]
	global_load_dword v1, v123, s[16:17] offset:512
	global_load_dword v2, v123, s[16:17] offset:1024
	global_load_dword v3, v123, s[16:17] offset:1536
	global_load_dword v4, v123, s[16:17] offset:2048
	global_load_dword v5, v123, s[16:17] offset:2560
	global_load_dword v6, v123, s[16:17] offset:3072
	global_load_dword v7, v123, s[16:17] offset:3584
	s_add_u32 s16, s16, 0x1000
	s_addc_u32 s17, s17, 0
	global_load_dword v8, v123, s[16:17]
	global_load_dword v9, v123, s[16:17] offset:512
	global_load_dword v10, v123, s[16:17] offset:1024
	global_load_dword v11, v123, s[16:17] offset:1536
	global_load_dword v12, v123, s[16:17] offset:2048
	global_load_dword v13, v123, s[16:17] offset:2560
	global_load_dword v14, v123, s[16:17] offset:3072
	global_load_dword v15, v123, s[16:17] offset:3584
	s_add_u32 s16, s16, 0x1000
	s_addc_u32 s17, s17, 0
	global_load_dword v16, v123, s[16:17]
	global_load_dword v17, v123, s[16:17] offset:512
	global_load_dword v18, v123, s[16:17] offset:1024
	global_load_dword v19, v123, s[16:17] offset:1536
	global_load_dword v20, v123, s[16:17] offset:2048
	global_load_dword v21, v123, s[16:17] offset:2560
	global_load_dword v22, v123, s[16:17] offset:3072
	global_load_dword v23, v123, s[16:17] offset:3584
	s_add_u32 s16, s16, 0x1000
	s_addc_u32 s17, s17, 0
	global_load_dword v24, v123, s[16:17]
	global_load_dword v25, v123, s[16:17] offset:512
	global_load_dword v26, v123, s[16:17] offset:1024
	global_load_dword v27, v123, s[16:17] offset:1536
	global_load_dword v28, v123, s[16:17] offset:2048
	global_load_dword v29, v123, s[16:17] offset:2560
	global_load_dword v30, v123, s[16:17] offset:3072
	global_load_dword v31, v123, s[16:17] offset:3584
	v_lshl_add_u32 v124, v129, 1, s4
	s_add_u32 s18, s90, 0x4a819600
	s_addc_u32 s19, s91, 0
	global_load_ushort v106, v124, s[18:19]
	s_add_u32 s18, s18, 0x880
	s_addc_u32 s19, s19, 0
	global_load_ushort v108, v124, s[18:19]
	s_add_u32 s18, s18, 0x880
	s_addc_u32 s19, s19, 0
	global_load_ushort v110, v124, s[18:19]
	s_add_u32 s18, s18, 0x880
	s_addc_u32 s19, s19, 0
	global_load_ushort v112, v124, s[18:19]
	s_add_u32 s18, s18, 0x880
	s_addc_u32 s19, s19, 0
	global_load_ushort v114, v124, s[18:19]
	s_add_u32 s18, s18, 0x880
	s_addc_u32 s19, s19, 0
	global_load_ushort v116, v124, s[18:19]
	s_add_u32 s18, s18, 0x880
	s_addc_u32 s19, s19, 0
	global_load_ushort v118, v124, s[18:19]
	s_add_u32 s18, s18, 0x880
	s_addc_u32 s19, s19, 0
	global_load_ushort v120, v124, s[18:19]
	v_lshlrev_b32_e32 v125, 9, v98
	v_lshl_add_u32 v125, v99, 3, v125
	s_waitcnt vmcnt(41)
	ds_write_b64 v125, v[102:103]
	s_waitcnt vmcnt(40)
	v_lshlrev_b32_e32 v102, 16, v104
	v_and_b32_e32 v103, 0xffff0000, v104
	ds_write_b64 v125, v[102:103] offset:4096
	v_lshlrev_b32_e32 v126, 7, v122
	s_waitcnt lgkmcnt(0)
	s_barrier
	v_lshlrev_b32_e32 v127, 9, v122
	v_lshl_add_u32 v127, v129, 2, v127
	v_add_u32_e32 v127, 0x2000, v127
	s_waitcnt vmcnt(0)
	v_lshlrev_b32_e32 v106, 16, v106
	v_lshlrev_b32_e32 v108, 16, v108
	v_lshlrev_b32_e32 v110, 16, v110
	v_lshlrev_b32_e32 v112, 16, v112
	v_lshlrev_b32_e32 v114, 16, v114
	v_lshlrev_b32_e32 v116, 16, v116
	v_lshlrev_b32_e32 v118, 16, v118
	v_lshlrev_b32_e32 v120, 16, v120
	ds_read_b128 v[32:35], v126 offset:0
	ds_read_b128 v[36:39], v126 offset:16
	ds_read_b128 v[40:43], v126 offset:32
	ds_read_b128 v[44:47], v126 offset:48
	ds_read_b128 v[48:51], v126 offset:64
	ds_read_b128 v[52:55], v126 offset:80
	ds_read_b128 v[56:59], v126 offset:96
	ds_read_b128 v[60:63], v126 offset:112
	ds_read_b128 v[66:69], v126 offset:4096
	ds_read_b128 v[70:73], v126 offset:4112
	ds_read_b128 v[74:77], v126 offset:4128
	ds_read_b128 v[78:81], v126 offset:4144
	s_waitcnt lgkmcnt(11)
	v_pk_add_f32 v[98:99], v[32:33], 1.0 op_sel_hi:[1,0] neg_lo:[1,0] neg_hi:[1,0]
	v_pk_mul_f32 v[98:99], v[98:99], v[106:107] op_sel_hi:[1,0]
	v_pk_fma_f32 v[0:1], v[0:1], v[32:33], v[98:99]
	v_pk_add_f32 v[100:101], v[34:35], 1.0 op_sel_hi:[1,0] neg_lo:[1,0] neg_hi:[1,0]
	v_pk_mul_f32 v[100:101], v[100:101], v[106:107] op_sel_hi:[1,0]
	v_pk_fma_f32 v[2:3], v[2:3], v[34:35], v[100:101]
	s_waitcnt lgkmcnt(10)
	v_pk_add_f32 v[102:103], v[36:37], 1.0 op_sel_hi:[1,0] neg_lo:[1,0] neg_hi:[1,0]
	v_pk_mul_f32 v[102:103], v[102:103], v[106:107] op_sel_hi:[1,0]
	v_pk_fma_f32 v[4:5], v[4:5], v[36:37], v[102:103]
	v_pk_add_f32 v[104:105], v[38:39], 1.0 op_sel_hi:[1,0] neg_lo:[1,0] neg_hi:[1,0]
	v_pk_mul_f32 v[104:105], v[104:105], v[106:107] op_sel_hi:[1,0]
	v_pk_fma_f32 v[6:7], v[6:7], v[38:39], v[104:105]
	s_waitcnt lgkmcnt(9)
	v_pk_add_f32 v[98:99], v[40:41], 1.0 op_sel_hi:[1,0] neg_lo:[1,0] neg_hi:[1,0]
	v_pk_mul_f32 v[98:99], v[98:99], v[106:107] op_sel_hi:[1,0]
	v_pk_fma_f32 v[8:9], v[8:9], v[40:41], v[98:99]
	v_pk_add_f32 v[100:101], v[42:43], 1.0 op_sel_hi:[1,0] neg_lo:[1,0] neg_hi:[1,0]
	v_pk_mul_f32 v[100:101], v[100:101], v[106:107] op_sel_hi:[1,0]
	v_pk_fma_f32 v[10:11], v[10:11], v[42:43], v[100:101]
	s_waitcnt lgkmcnt(8)
	v_pk_add_f32 v[102:103], v[44:45], 1.0 op_sel_hi:[1,0] neg_lo:[1,0] neg_hi:[1,0]
	v_pk_mul_f32 v[102:103], v[102:103], v[106:107] op_sel_hi:[1,0]
	v_pk_fma_f32 v[12:13], v[12:13], v[44:45], v[102:103]
	v_pk_add_f32 v[104:105], v[46:47], 1.0 op_sel_hi:[1,0] neg_lo:[1,0] neg_hi:[1,0]
	v_pk_mul_f32 v[104:105], v[104:105], v[106:107] op_sel_hi:[1,0]
	v_pk_fma_f32 v[14:15], v[14:15], v[46:47], v[104:105]
	ds_read_b128 v[82:85], v126 offset:4160
	ds_read_b128 v[86:89], v126 offset:4176
	ds_read_b128 v[90:93], v126 offset:4192
	ds_read_b128 v[94:97], v126 offset:4208
	s_waitcnt lgkmcnt(11)
	v_pk_add_f32 v[98:99], v[48:49], 1.0 op_sel_hi:[1,0] neg_lo:[1,0] neg_hi:[1,0]
	v_pk_mul_f32 v[98:99], v[98:99], v[106:107] op_sel_hi:[1,0]
	v_pk_fma_f32 v[16:17], v[16:17], v[48:49], v[98:99]
	v_pk_add_f32 v[100:101], v[50:51], 1.0 op_sel_hi:[1,0] neg_lo:[1,0] neg_hi:[1,0]
	v_pk_mul_f32 v[100:101], v[100:101], v[106:107] op_sel_hi:[1,0]
	v_pk_fma_f32 v[18:19], v[18:19], v[50:51], v[100:101]
	s_waitcnt lgkmcnt(10)
	v_pk_add_f32 v[102:103], v[52:53], 1.0 op_sel_hi:[1,0] neg_lo:[1,0] neg_hi:[1,0]
	v_pk_mul_f32 v[102:103], v[102:103], v[106:107] op_sel_hi:[1,0]
	v_pk_fma_f32 v[20:21], v[20:21], v[52:53], v[102:103]
	v_pk_add_f32 v[104:105], v[54:55], 1.0 op_sel_hi:[1,0] neg_lo:[1,0] neg_hi:[1,0]
	v_pk_mul_f32 v[104:105], v[104:105], v[106:107] op_sel_hi:[1,0]
	v_pk_fma_f32 v[22:23], v[22:23], v[54:55], v[104:105]
	s_waitcnt lgkmcnt(9)
	v_pk_add_f32 v[98:99], v[56:57], 1.0 op_sel_hi:[1,0] neg_lo:[1,0] neg_hi:[1,0]
	v_pk_mul_f32 v[98:99], v[98:99], v[106:107] op_sel_hi:[1,0]
	v_pk_fma_f32 v[24:25], v[24:25], v[56:57], v[98:99]
	v_pk_add_f32 v[100:101], v[58:59], 1.0 op_sel_hi:[1,0] neg_lo:[1,0] neg_hi:[1,0]
	v_pk_mul_f32 v[100:101], v[100:101], v[106:107] op_sel_hi:[1,0]
	v_pk_fma_f32 v[26:27], v[26:27], v[58:59], v[100:101]
	s_waitcnt lgkmcnt(8)
	v_pk_add_f32 v[102:103], v[60:61], 1.0 op_sel_hi:[1,0] neg_lo:[1,0] neg_hi:[1,0]
	v_pk_mul_f32 v[102:103], v[102:103], v[106:107] op_sel_hi:[1,0]
	v_pk_fma_f32 v[28:29], v[28:29], v[60:61], v[102:103]
	v_pk_add_f32 v[104:105], v[62:63], 1.0 op_sel_hi:[1,0] neg_lo:[1,0] neg_hi:[1,0]
	v_pk_mul_f32 v[104:105], v[104:105], v[106:107] op_sel_hi:[1,0]
	v_pk_fma_f32 v[30:31], v[30:31], v[62:63], v[104:105]
	s_waitcnt lgkmcnt(0)
	v_fma_f32 v128, v66, v0, 0
	v_fmac_f32_e32 v128, v67, v1
	v_fmac_f32_e32 v128, v68, v2
	v_fmac_f32_e32 v128, v69, v3
	v_fmac_f32_e32 v128, v70, v4
	v_fmac_f32_e32 v128, v71, v5
	v_fmac_f32_e32 v128, v72, v6
	v_fmac_f32_e32 v128, v73, v7
	v_fmac_f32_e32 v128, v74, v8
	v_fmac_f32_e32 v128, v75, v9
	v_fmac_f32_e32 v128, v76, v10
	v_fmac_f32_e32 v128, v77, v11
	v_fmac_f32_e32 v128, v78, v12
	v_fmac_f32_e32 v128, v79, v13
	v_fmac_f32_e32 v128, v80, v14
	v_fmac_f32_e32 v128, v81, v15
	v_fmac_f32_e32 v128, v82, v16
	v_fmac_f32_e32 v128, v83, v17
	v_fmac_f32_e32 v128, v84, v18
	v_fmac_f32_e32 v128, v85, v19
	v_fmac_f32_e32 v128, v86, v20
	v_fmac_f32_e32 v128, v87, v21
	v_fmac_f32_e32 v128, v88, v22
	v_fmac_f32_e32 v128, v89, v23
	v_fmac_f32_e32 v128, v90, v24
	v_fmac_f32_e32 v128, v91, v25
	v_fmac_f32_e32 v128, v92, v26
	v_fmac_f32_e32 v128, v93, v27
	v_fmac_f32_e32 v128, v94, v28
	v_fmac_f32_e32 v128, v95, v29
	v_fmac_f32_e32 v128, v96, v30
	v_fmac_f32_e32 v128, v97, v31
	ds_write_b32 v127, v128 offset:0
	ds_read_b128 v[32:35], v126 offset:512
	ds_read_b128 v[36:39], v126 offset:528
	ds_read_b128 v[40:43], v126 offset:544
	ds_read_b128 v[44:47], v126 offset:560
	ds_read_b128 v[48:51], v126 offset:576
	ds_read_b128 v[52:55], v126 offset:592
	ds_read_b128 v[56:59], v126 offset:608
	ds_read_b128 v[60:63], v126 offset:624
	ds_read_b128 v[66:69], v126 offset:4608
	ds_read_b128 v[70:73], v126 offset:4624
	ds_read_b128 v[74:77], v126 offset:4640
	ds_read_b128 v[78:81], v126 offset:4656
	s_waitcnt lgkmcnt(11)
	v_pk_add_f32 v[98:99], v[32:33], 1.0 op_sel_hi:[1,0] neg_lo:[1,0] neg_hi:[1,0]
	v_pk_mul_f32 v[98:99], v[98:99], v[108:109] op_sel_hi:[1,0]
	v_pk_fma_f32 v[0:1], v[0:1], v[32:33], v[98:99]
	v_pk_add_f32 v[100:101], v[34:35], 1.0 op_sel_hi:[1,0] neg_lo:[1,0] neg_hi:[1,0]
	v_pk_mul_f32 v[100:101], v[100:101], v[108:109] op_sel_hi:[1,0]
	v_pk_fma_f32 v[2:3], v[2:3], v[34:35], v[100:101]
	s_waitcnt lgkmcnt(10)
	v_pk_add_f32 v[102:103], v[36:37], 1.0 op_sel_hi:[1,0] neg_lo:[1,0] neg_hi:[1,0]
	v_pk_mul_f32 v[102:103], v[102:103], v[108:109] op_sel_hi:[1,0]
	v_pk_fma_f32 v[4:5], v[4:5], v[36:37], v[102:103]
	v_pk_add_f32 v[104:105], v[38:39], 1.0 op_sel_hi:[1,0] neg_lo:[1,0] neg_hi:[1,0]
	v_pk_mul_f32 v[104:105], v[104:105], v[108:109] op_sel_hi:[1,0]
	v_pk_fma_f32 v[6:7], v[6:7], v[38:39], v[104:105]
	s_waitcnt lgkmcnt(9)
	v_pk_add_f32 v[98:99], v[40:41], 1.0 op_sel_hi:[1,0] neg_lo:[1,0] neg_hi:[1,0]
	v_pk_mul_f32 v[98:99], v[98:99], v[108:109] op_sel_hi:[1,0]
	v_pk_fma_f32 v[8:9], v[8:9], v[40:41], v[98:99]
	v_pk_add_f32 v[100:101], v[42:43], 1.0 op_sel_hi:[1,0] neg_lo:[1,0] neg_hi:[1,0]
	v_pk_mul_f32 v[100:101], v[100:101], v[108:109] op_sel_hi:[1,0]
	v_pk_fma_f32 v[10:11], v[10:11], v[42:43], v[100:101]
	s_waitcnt lgkmcnt(8)
	v_pk_add_f32 v[102:103], v[44:45], 1.0 op_sel_hi:[1,0] neg_lo:[1,0] neg_hi:[1,0]
	v_pk_mul_f32 v[102:103], v[102:103], v[108:109] op_sel_hi:[1,0]
	v_pk_fma_f32 v[12:13], v[12:13], v[44:45], v[102:103]
	v_pk_add_f32 v[104:105], v[46:47], 1.0 op_sel_hi:[1,0] neg_lo:[1,0] neg_hi:[1,0]
	v_pk_mul_f32 v[104:105], v[104:105], v[108:109] op_sel_hi:[1,0]
	v_pk_fma_f32 v[14:15], v[14:15], v[46:47], v[104:105]
	ds_read_b128 v[82:85], v126 offset:4672
	ds_read_b128 v[86:89], v126 offset:4688
	ds_read_b128 v[90:93], v126 offset:4704
	ds_read_b128 v[94:97], v126 offset:4720
	s_waitcnt lgkmcnt(11)
	v_pk_add_f32 v[98:99], v[48:49], 1.0 op_sel_hi:[1,0] neg_lo:[1,0] neg_hi:[1,0]
	v_pk_mul_f32 v[98:99], v[98:99], v[108:109] op_sel_hi:[1,0]
	v_pk_fma_f32 v[16:17], v[16:17], v[48:49], v[98:99]
	v_pk_add_f32 v[100:101], v[50:51], 1.0 op_sel_hi:[1,0] neg_lo:[1,0] neg_hi:[1,0]
	v_pk_mul_f32 v[100:101], v[100:101], v[108:109] op_sel_hi:[1,0]
	v_pk_fma_f32 v[18:19], v[18:19], v[50:51], v[100:101]
	s_waitcnt lgkmcnt(10)
	v_pk_add_f32 v[102:103], v[52:53], 1.0 op_sel_hi:[1,0] neg_lo:[1,0] neg_hi:[1,0]
	v_pk_mul_f32 v[102:103], v[102:103], v[108:109] op_sel_hi:[1,0]
	v_pk_fma_f32 v[20:21], v[20:21], v[52:53], v[102:103]
	v_pk_add_f32 v[104:105], v[54:55], 1.0 op_sel_hi:[1,0] neg_lo:[1,0] neg_hi:[1,0]
	v_pk_mul_f32 v[104:105], v[104:105], v[108:109] op_sel_hi:[1,0]
	v_pk_fma_f32 v[22:23], v[22:23], v[54:55], v[104:105]
	s_waitcnt lgkmcnt(9)
	v_pk_add_f32 v[98:99], v[56:57], 1.0 op_sel_hi:[1,0] neg_lo:[1,0] neg_hi:[1,0]
	v_pk_mul_f32 v[98:99], v[98:99], v[108:109] op_sel_hi:[1,0]
	v_pk_fma_f32 v[24:25], v[24:25], v[56:57], v[98:99]
	v_pk_add_f32 v[100:101], v[58:59], 1.0 op_sel_hi:[1,0] neg_lo:[1,0] neg_hi:[1,0]
	v_pk_mul_f32 v[100:101], v[100:101], v[108:109] op_sel_hi:[1,0]
	v_pk_fma_f32 v[26:27], v[26:27], v[58:59], v[100:101]
	s_waitcnt lgkmcnt(8)
	v_pk_add_f32 v[102:103], v[60:61], 1.0 op_sel_hi:[1,0] neg_lo:[1,0] neg_hi:[1,0]
	v_pk_mul_f32 v[102:103], v[102:103], v[108:109] op_sel_hi:[1,0]
	v_pk_fma_f32 v[28:29], v[28:29], v[60:61], v[102:103]
	v_pk_add_f32 v[104:105], v[62:63], 1.0 op_sel_hi:[1,0] neg_lo:[1,0] neg_hi:[1,0]
	v_pk_mul_f32 v[104:105], v[104:105], v[108:109] op_sel_hi:[1,0]
	v_pk_fma_f32 v[30:31], v[30:31], v[62:63], v[104:105]
	s_waitcnt lgkmcnt(0)
	v_fma_f32 v128, v66, v0, 0
	v_fmac_f32_e32 v128, v67, v1
	v_fmac_f32_e32 v128, v68, v2
	v_fmac_f32_e32 v128, v69, v3
	v_fmac_f32_e32 v128, v70, v4
	v_fmac_f32_e32 v128, v71, v5
	v_fmac_f32_e32 v128, v72, v6
	v_fmac_f32_e32 v128, v73, v7
	v_fmac_f32_e32 v128, v74, v8
	v_fmac_f32_e32 v128, v75, v9
	v_fmac_f32_e32 v128, v76, v10
	v_fmac_f32_e32 v128, v77, v11
	v_fmac_f32_e32 v128, v78, v12
	v_fmac_f32_e32 v128, v79, v13
	v_fmac_f32_e32 v128, v80, v14
	v_fmac_f32_e32 v128, v81, v15
	v_fmac_f32_e32 v128, v82, v16
	v_fmac_f32_e32 v128, v83, v17
	v_fmac_f32_e32 v128, v84, v18
	v_fmac_f32_e32 v128, v85, v19
	v_fmac_f32_e32 v128, v86, v20
	v_fmac_f32_e32 v128, v87, v21
	v_fmac_f32_e32 v128, v88, v22
	v_fmac_f32_e32 v128, v89, v23
	v_fmac_f32_e32 v128, v90, v24
	v_fmac_f32_e32 v128, v91, v25
	v_fmac_f32_e32 v128, v92, v26
	v_fmac_f32_e32 v128, v93, v27
	v_fmac_f32_e32 v128, v94, v28
	v_fmac_f32_e32 v128, v95, v29
	v_fmac_f32_e32 v128, v96, v30
	v_fmac_f32_e32 v128, v97, v31
	ds_write_b32 v127, v128 offset:2048
	ds_read_b128 v[32:35], v126 offset:1024
	ds_read_b128 v[36:39], v126 offset:1040
	ds_read_b128 v[40:43], v126 offset:1056
	ds_read_b128 v[44:47], v126 offset:1072
	ds_read_b128 v[48:51], v126 offset:1088
	ds_read_b128 v[52:55], v126 offset:1104
	ds_read_b128 v[56:59], v126 offset:1120
	ds_read_b128 v[60:63], v126 offset:1136
	ds_read_b128 v[66:69], v126 offset:5120
	ds_read_b128 v[70:73], v126 offset:5136
	ds_read_b128 v[74:77], v126 offset:5152
	ds_read_b128 v[78:81], v126 offset:5168
	s_waitcnt lgkmcnt(11)
	v_pk_add_f32 v[98:99], v[32:33], 1.0 op_sel_hi:[1,0] neg_lo:[1,0] neg_hi:[1,0]
	v_pk_mul_f32 v[98:99], v[98:99], v[110:111] op_sel_hi:[1,0]
	v_pk_fma_f32 v[0:1], v[0:1], v[32:33], v[98:99]
	v_pk_add_f32 v[100:101], v[34:35], 1.0 op_sel_hi:[1,0] neg_lo:[1,0] neg_hi:[1,0]
	v_pk_mul_f32 v[100:101], v[100:101], v[110:111] op_sel_hi:[1,0]
	v_pk_fma_f32 v[2:3], v[2:3], v[34:35], v[100:101]
	s_waitcnt lgkmcnt(10)
	v_pk_add_f32 v[102:103], v[36:37], 1.0 op_sel_hi:[1,0] neg_lo:[1,0] neg_hi:[1,0]
	v_pk_mul_f32 v[102:103], v[102:103], v[110:111] op_sel_hi:[1,0]
	v_pk_fma_f32 v[4:5], v[4:5], v[36:37], v[102:103]
	v_pk_add_f32 v[104:105], v[38:39], 1.0 op_sel_hi:[1,0] neg_lo:[1,0] neg_hi:[1,0]
	v_pk_mul_f32 v[104:105], v[104:105], v[110:111] op_sel_hi:[1,0]
	v_pk_fma_f32 v[6:7], v[6:7], v[38:39], v[104:105]
	s_waitcnt lgkmcnt(9)
	v_pk_add_f32 v[98:99], v[40:41], 1.0 op_sel_hi:[1,0] neg_lo:[1,0] neg_hi:[1,0]
	v_pk_mul_f32 v[98:99], v[98:99], v[110:111] op_sel_hi:[1,0]
	v_pk_fma_f32 v[8:9], v[8:9], v[40:41], v[98:99]
	v_pk_add_f32 v[100:101], v[42:43], 1.0 op_sel_hi:[1,0] neg_lo:[1,0] neg_hi:[1,0]
	v_pk_mul_f32 v[100:101], v[100:101], v[110:111] op_sel_hi:[1,0]
	v_pk_fma_f32 v[10:11], v[10:11], v[42:43], v[100:101]
	s_waitcnt lgkmcnt(8)
	v_pk_add_f32 v[102:103], v[44:45], 1.0 op_sel_hi:[1,0] neg_lo:[1,0] neg_hi:[1,0]
	v_pk_mul_f32 v[102:103], v[102:103], v[110:111] op_sel_hi:[1,0]
	v_pk_fma_f32 v[12:13], v[12:13], v[44:45], v[102:103]
	v_pk_add_f32 v[104:105], v[46:47], 1.0 op_sel_hi:[1,0] neg_lo:[1,0] neg_hi:[1,0]
	v_pk_mul_f32 v[104:105], v[104:105], v[110:111] op_sel_hi:[1,0]
	v_pk_fma_f32 v[14:15], v[14:15], v[46:47], v[104:105]
	ds_read_b128 v[82:85], v126 offset:5184
	ds_read_b128 v[86:89], v126 offset:5200
	ds_read_b128 v[90:93], v126 offset:5216
	ds_read_b128 v[94:97], v126 offset:5232
	s_waitcnt lgkmcnt(11)
	v_pk_add_f32 v[98:99], v[48:49], 1.0 op_sel_hi:[1,0] neg_lo:[1,0] neg_hi:[1,0]
	v_pk_mul_f32 v[98:99], v[98:99], v[110:111] op_sel_hi:[1,0]
	v_pk_fma_f32 v[16:17], v[16:17], v[48:49], v[98:99]
	v_pk_add_f32 v[100:101], v[50:51], 1.0 op_sel_hi:[1,0] neg_lo:[1,0] neg_hi:[1,0]
	v_pk_mul_f32 v[100:101], v[100:101], v[110:111] op_sel_hi:[1,0]
	v_pk_fma_f32 v[18:19], v[18:19], v[50:51], v[100:101]
	s_waitcnt lgkmcnt(10)
	v_pk_add_f32 v[102:103], v[52:53], 1.0 op_sel_hi:[1,0] neg_lo:[1,0] neg_hi:[1,0]
	v_pk_mul_f32 v[102:103], v[102:103], v[110:111] op_sel_hi:[1,0]
	v_pk_fma_f32 v[20:21], v[20:21], v[52:53], v[102:103]
	v_pk_add_f32 v[104:105], v[54:55], 1.0 op_sel_hi:[1,0] neg_lo:[1,0] neg_hi:[1,0]
	v_pk_mul_f32 v[104:105], v[104:105], v[110:111] op_sel_hi:[1,0]
	v_pk_fma_f32 v[22:23], v[22:23], v[54:55], v[104:105]
	s_waitcnt lgkmcnt(9)
	v_pk_add_f32 v[98:99], v[56:57], 1.0 op_sel_hi:[1,0] neg_lo:[1,0] neg_hi:[1,0]
	v_pk_mul_f32 v[98:99], v[98:99], v[110:111] op_sel_hi:[1,0]
	v_pk_fma_f32 v[24:25], v[24:25], v[56:57], v[98:99]
	v_pk_add_f32 v[100:101], v[58:59], 1.0 op_sel_hi:[1,0] neg_lo:[1,0] neg_hi:[1,0]
	v_pk_mul_f32 v[100:101], v[100:101], v[110:111] op_sel_hi:[1,0]
	v_pk_fma_f32 v[26:27], v[26:27], v[58:59], v[100:101]
	s_waitcnt lgkmcnt(8)
	v_pk_add_f32 v[102:103], v[60:61], 1.0 op_sel_hi:[1,0] neg_lo:[1,0] neg_hi:[1,0]
	v_pk_mul_f32 v[102:103], v[102:103], v[110:111] op_sel_hi:[1,0]
	v_pk_fma_f32 v[28:29], v[28:29], v[60:61], v[102:103]
	v_pk_add_f32 v[104:105], v[62:63], 1.0 op_sel_hi:[1,0] neg_lo:[1,0] neg_hi:[1,0]
	v_pk_mul_f32 v[104:105], v[104:105], v[110:111] op_sel_hi:[1,0]
	v_pk_fma_f32 v[30:31], v[30:31], v[62:63], v[104:105]
	s_waitcnt lgkmcnt(0)
	v_fma_f32 v128, v66, v0, 0
	v_fmac_f32_e32 v128, v67, v1
	v_fmac_f32_e32 v128, v68, v2
	v_fmac_f32_e32 v128, v69, v3
	v_fmac_f32_e32 v128, v70, v4
	v_fmac_f32_e32 v128, v71, v5
	v_fmac_f32_e32 v128, v72, v6
	v_fmac_f32_e32 v128, v73, v7
	v_fmac_f32_e32 v128, v74, v8
	v_fmac_f32_e32 v128, v75, v9
	v_fmac_f32_e32 v128, v76, v10
	v_fmac_f32_e32 v128, v77, v11
	v_fmac_f32_e32 v128, v78, v12
	v_fmac_f32_e32 v128, v79, v13
	v_fmac_f32_e32 v128, v80, v14
	v_fmac_f32_e32 v128, v81, v15
	v_fmac_f32_e32 v128, v82, v16
	v_fmac_f32_e32 v128, v83, v17
	v_fmac_f32_e32 v128, v84, v18
	v_fmac_f32_e32 v128, v85, v19
	v_fmac_f32_e32 v128, v86, v20
	v_fmac_f32_e32 v128, v87, v21
	v_fmac_f32_e32 v128, v88, v22
	v_fmac_f32_e32 v128, v89, v23
	v_fmac_f32_e32 v128, v90, v24
	v_fmac_f32_e32 v128, v91, v25
	v_fmac_f32_e32 v128, v92, v26
	v_fmac_f32_e32 v128, v93, v27
	v_fmac_f32_e32 v128, v94, v28
	v_fmac_f32_e32 v128, v95, v29
	v_fmac_f32_e32 v128, v96, v30
	v_fmac_f32_e32 v128, v97, v31
	ds_write_b32 v127, v128 offset:4096
	ds_read_b128 v[32:35], v126 offset:1536
	ds_read_b128 v[36:39], v126 offset:1552
	ds_read_b128 v[40:43], v126 offset:1568
	ds_read_b128 v[44:47], v126 offset:1584
	ds_read_b128 v[48:51], v126 offset:1600
	ds_read_b128 v[52:55], v126 offset:1616
	ds_read_b128 v[56:59], v126 offset:1632
	ds_read_b128 v[60:63], v126 offset:1648
	ds_read_b128 v[66:69], v126 offset:5632
	ds_read_b128 v[70:73], v126 offset:5648
	ds_read_b128 v[74:77], v126 offset:5664
	ds_read_b128 v[78:81], v126 offset:5680
	s_waitcnt lgkmcnt(11)
	v_pk_add_f32 v[98:99], v[32:33], 1.0 op_sel_hi:[1,0] neg_lo:[1,0] neg_hi:[1,0]
	v_pk_mul_f32 v[98:99], v[98:99], v[112:113] op_sel_hi:[1,0]
	v_pk_fma_f32 v[0:1], v[0:1], v[32:33], v[98:99]
	v_pk_add_f32 v[100:101], v[34:35], 1.0 op_sel_hi:[1,0] neg_lo:[1,0] neg_hi:[1,0]
	v_pk_mul_f32 v[100:101], v[100:101], v[112:113] op_sel_hi:[1,0]
	v_pk_fma_f32 v[2:3], v[2:3], v[34:35], v[100:101]
	s_waitcnt lgkmcnt(10)
	v_pk_add_f32 v[102:103], v[36:37], 1.0 op_sel_hi:[1,0] neg_lo:[1,0] neg_hi:[1,0]
	v_pk_mul_f32 v[102:103], v[102:103], v[112:113] op_sel_hi:[1,0]
	v_pk_fma_f32 v[4:5], v[4:5], v[36:37], v[102:103]
	v_pk_add_f32 v[104:105], v[38:39], 1.0 op_sel_hi:[1,0] neg_lo:[1,0] neg_hi:[1,0]
	v_pk_mul_f32 v[104:105], v[104:105], v[112:113] op_sel_hi:[1,0]
	v_pk_fma_f32 v[6:7], v[6:7], v[38:39], v[104:105]
	s_waitcnt lgkmcnt(9)
	v_pk_add_f32 v[98:99], v[40:41], 1.0 op_sel_hi:[1,0] neg_lo:[1,0] neg_hi:[1,0]
	v_pk_mul_f32 v[98:99], v[98:99], v[112:113] op_sel_hi:[1,0]
	v_pk_fma_f32 v[8:9], v[8:9], v[40:41], v[98:99]
	v_pk_add_f32 v[100:101], v[42:43], 1.0 op_sel_hi:[1,0] neg_lo:[1,0] neg_hi:[1,0]
	v_pk_mul_f32 v[100:101], v[100:101], v[112:113] op_sel_hi:[1,0]
	v_pk_fma_f32 v[10:11], v[10:11], v[42:43], v[100:101]
	s_waitcnt lgkmcnt(8)
	v_pk_add_f32 v[102:103], v[44:45], 1.0 op_sel_hi:[1,0] neg_lo:[1,0] neg_hi:[1,0]
	v_pk_mul_f32 v[102:103], v[102:103], v[112:113] op_sel_hi:[1,0]
	v_pk_fma_f32 v[12:13], v[12:13], v[44:45], v[102:103]
	v_pk_add_f32 v[104:105], v[46:47], 1.0 op_sel_hi:[1,0] neg_lo:[1,0] neg_hi:[1,0]
	v_pk_mul_f32 v[104:105], v[104:105], v[112:113] op_sel_hi:[1,0]
	v_pk_fma_f32 v[14:15], v[14:15], v[46:47], v[104:105]
	ds_read_b128 v[82:85], v126 offset:5696
	ds_read_b128 v[86:89], v126 offset:5712
	ds_read_b128 v[90:93], v126 offset:5728
	ds_read_b128 v[94:97], v126 offset:5744
	s_waitcnt lgkmcnt(11)
	v_pk_add_f32 v[98:99], v[48:49], 1.0 op_sel_hi:[1,0] neg_lo:[1,0] neg_hi:[1,0]
	v_pk_mul_f32 v[98:99], v[98:99], v[112:113] op_sel_hi:[1,0]
	v_pk_fma_f32 v[16:17], v[16:17], v[48:49], v[98:99]
	v_pk_add_f32 v[100:101], v[50:51], 1.0 op_sel_hi:[1,0] neg_lo:[1,0] neg_hi:[1,0]
	v_pk_mul_f32 v[100:101], v[100:101], v[112:113] op_sel_hi:[1,0]
	v_pk_fma_f32 v[18:19], v[18:19], v[50:51], v[100:101]
	s_waitcnt lgkmcnt(10)
	v_pk_add_f32 v[102:103], v[52:53], 1.0 op_sel_hi:[1,0] neg_lo:[1,0] neg_hi:[1,0]
	v_pk_mul_f32 v[102:103], v[102:103], v[112:113] op_sel_hi:[1,0]
	v_pk_fma_f32 v[20:21], v[20:21], v[52:53], v[102:103]
	v_pk_add_f32 v[104:105], v[54:55], 1.0 op_sel_hi:[1,0] neg_lo:[1,0] neg_hi:[1,0]
	v_pk_mul_f32 v[104:105], v[104:105], v[112:113] op_sel_hi:[1,0]
	v_pk_fma_f32 v[22:23], v[22:23], v[54:55], v[104:105]
	s_waitcnt lgkmcnt(9)
	v_pk_add_f32 v[98:99], v[56:57], 1.0 op_sel_hi:[1,0] neg_lo:[1,0] neg_hi:[1,0]
	v_pk_mul_f32 v[98:99], v[98:99], v[112:113] op_sel_hi:[1,0]
	v_pk_fma_f32 v[24:25], v[24:25], v[56:57], v[98:99]
	v_pk_add_f32 v[100:101], v[58:59], 1.0 op_sel_hi:[1,0] neg_lo:[1,0] neg_hi:[1,0]
	v_pk_mul_f32 v[100:101], v[100:101], v[112:113] op_sel_hi:[1,0]
	v_pk_fma_f32 v[26:27], v[26:27], v[58:59], v[100:101]
	s_waitcnt lgkmcnt(8)
	v_pk_add_f32 v[102:103], v[60:61], 1.0 op_sel_hi:[1,0] neg_lo:[1,0] neg_hi:[1,0]
	v_pk_mul_f32 v[102:103], v[102:103], v[112:113] op_sel_hi:[1,0]
	v_pk_fma_f32 v[28:29], v[28:29], v[60:61], v[102:103]
	v_pk_add_f32 v[104:105], v[62:63], 1.0 op_sel_hi:[1,0] neg_lo:[1,0] neg_hi:[1,0]
	v_pk_mul_f32 v[104:105], v[104:105], v[112:113] op_sel_hi:[1,0]
	v_pk_fma_f32 v[30:31], v[30:31], v[62:63], v[104:105]
	s_waitcnt lgkmcnt(0)
	v_fma_f32 v128, v66, v0, 0
	v_fmac_f32_e32 v128, v67, v1
	v_fmac_f32_e32 v128, v68, v2
	v_fmac_f32_e32 v128, v69, v3
	v_fmac_f32_e32 v128, v70, v4
	v_fmac_f32_e32 v128, v71, v5
	v_fmac_f32_e32 v128, v72, v6
	v_fmac_f32_e32 v128, v73, v7
	v_fmac_f32_e32 v128, v74, v8
	v_fmac_f32_e32 v128, v75, v9
	v_fmac_f32_e32 v128, v76, v10
	v_fmac_f32_e32 v128, v77, v11
	v_fmac_f32_e32 v128, v78, v12
	v_fmac_f32_e32 v128, v79, v13
	v_fmac_f32_e32 v128, v80, v14
	v_fmac_f32_e32 v128, v81, v15
	v_fmac_f32_e32 v128, v82, v16
	v_fmac_f32_e32 v128, v83, v17
	v_fmac_f32_e32 v128, v84, v18
	v_fmac_f32_e32 v128, v85, v19
	v_fmac_f32_e32 v128, v86, v20
	v_fmac_f32_e32 v128, v87, v21
	v_fmac_f32_e32 v128, v88, v22
	v_fmac_f32_e32 v128, v89, v23
	v_fmac_f32_e32 v128, v90, v24
	v_fmac_f32_e32 v128, v91, v25
	v_fmac_f32_e32 v128, v92, v26
	v_fmac_f32_e32 v128, v93, v27
	v_fmac_f32_e32 v128, v94, v28
	v_fmac_f32_e32 v128, v95, v29
	v_fmac_f32_e32 v128, v96, v30
	v_fmac_f32_e32 v128, v97, v31
	ds_write_b32 v127, v128 offset:6144
	ds_read_b128 v[32:35], v126 offset:2048
	ds_read_b128 v[36:39], v126 offset:2064
	ds_read_b128 v[40:43], v126 offset:2080
	ds_read_b128 v[44:47], v126 offset:2096
	ds_read_b128 v[48:51], v126 offset:2112
	ds_read_b128 v[52:55], v126 offset:2128
	ds_read_b128 v[56:59], v126 offset:2144
	ds_read_b128 v[60:63], v126 offset:2160
	ds_read_b128 v[66:69], v126 offset:6144
	ds_read_b128 v[70:73], v126 offset:6160
	ds_read_b128 v[74:77], v126 offset:6176
	ds_read_b128 v[78:81], v126 offset:6192
	s_waitcnt lgkmcnt(11)
	v_pk_add_f32 v[98:99], v[32:33], 1.0 op_sel_hi:[1,0] neg_lo:[1,0] neg_hi:[1,0]
	v_pk_mul_f32 v[98:99], v[98:99], v[114:115] op_sel_hi:[1,0]
	v_pk_fma_f32 v[0:1], v[0:1], v[32:33], v[98:99]
	v_pk_add_f32 v[100:101], v[34:35], 1.0 op_sel_hi:[1,0] neg_lo:[1,0] neg_hi:[1,0]
	v_pk_mul_f32 v[100:101], v[100:101], v[114:115] op_sel_hi:[1,0]
	v_pk_fma_f32 v[2:3], v[2:3], v[34:35], v[100:101]
	s_waitcnt lgkmcnt(10)
	v_pk_add_f32 v[102:103], v[36:37], 1.0 op_sel_hi:[1,0] neg_lo:[1,0] neg_hi:[1,0]
	v_pk_mul_f32 v[102:103], v[102:103], v[114:115] op_sel_hi:[1,0]
	v_pk_fma_f32 v[4:5], v[4:5], v[36:37], v[102:103]
	v_pk_add_f32 v[104:105], v[38:39], 1.0 op_sel_hi:[1,0] neg_lo:[1,0] neg_hi:[1,0]
	v_pk_mul_f32 v[104:105], v[104:105], v[114:115] op_sel_hi:[1,0]
	v_pk_fma_f32 v[6:7], v[6:7], v[38:39], v[104:105]
	s_waitcnt lgkmcnt(9)
	v_pk_add_f32 v[98:99], v[40:41], 1.0 op_sel_hi:[1,0] neg_lo:[1,0] neg_hi:[1,0]
	v_pk_mul_f32 v[98:99], v[98:99], v[114:115] op_sel_hi:[1,0]
	v_pk_fma_f32 v[8:9], v[8:9], v[40:41], v[98:99]
	v_pk_add_f32 v[100:101], v[42:43], 1.0 op_sel_hi:[1,0] neg_lo:[1,0] neg_hi:[1,0]
	v_pk_mul_f32 v[100:101], v[100:101], v[114:115] op_sel_hi:[1,0]
	v_pk_fma_f32 v[10:11], v[10:11], v[42:43], v[100:101]
	s_waitcnt lgkmcnt(8)
	v_pk_add_f32 v[102:103], v[44:45], 1.0 op_sel_hi:[1,0] neg_lo:[1,0] neg_hi:[1,0]
	v_pk_mul_f32 v[102:103], v[102:103], v[114:115] op_sel_hi:[1,0]
	v_pk_fma_f32 v[12:13], v[12:13], v[44:45], v[102:103]
	v_pk_add_f32 v[104:105], v[46:47], 1.0 op_sel_hi:[1,0] neg_lo:[1,0] neg_hi:[1,0]
	v_pk_mul_f32 v[104:105], v[104:105], v[114:115] op_sel_hi:[1,0]
	v_pk_fma_f32 v[14:15], v[14:15], v[46:47], v[104:105]
	ds_read_b128 v[82:85], v126 offset:6208
	ds_read_b128 v[86:89], v126 offset:6224
	ds_read_b128 v[90:93], v126 offset:6240
	ds_read_b128 v[94:97], v126 offset:6256
	s_waitcnt lgkmcnt(11)
	v_pk_add_f32 v[98:99], v[48:49], 1.0 op_sel_hi:[1,0] neg_lo:[1,0] neg_hi:[1,0]
	v_pk_mul_f32 v[98:99], v[98:99], v[114:115] op_sel_hi:[1,0]
	v_pk_fma_f32 v[16:17], v[16:17], v[48:49], v[98:99]
	v_pk_add_f32 v[100:101], v[50:51], 1.0 op_sel_hi:[1,0] neg_lo:[1,0] neg_hi:[1,0]
	v_pk_mul_f32 v[100:101], v[100:101], v[114:115] op_sel_hi:[1,0]
	v_pk_fma_f32 v[18:19], v[18:19], v[50:51], v[100:101]
	s_waitcnt lgkmcnt(10)
	v_pk_add_f32 v[102:103], v[52:53], 1.0 op_sel_hi:[1,0] neg_lo:[1,0] neg_hi:[1,0]
	v_pk_mul_f32 v[102:103], v[102:103], v[114:115] op_sel_hi:[1,0]
	v_pk_fma_f32 v[20:21], v[20:21], v[52:53], v[102:103]
	v_pk_add_f32 v[104:105], v[54:55], 1.0 op_sel_hi:[1,0] neg_lo:[1,0] neg_hi:[1,0]
	v_pk_mul_f32 v[104:105], v[104:105], v[114:115] op_sel_hi:[1,0]
	v_pk_fma_f32 v[22:23], v[22:23], v[54:55], v[104:105]
	s_waitcnt lgkmcnt(9)
	v_pk_add_f32 v[98:99], v[56:57], 1.0 op_sel_hi:[1,0] neg_lo:[1,0] neg_hi:[1,0]
	v_pk_mul_f32 v[98:99], v[98:99], v[114:115] op_sel_hi:[1,0]
	v_pk_fma_f32 v[24:25], v[24:25], v[56:57], v[98:99]
	v_pk_add_f32 v[100:101], v[58:59], 1.0 op_sel_hi:[1,0] neg_lo:[1,0] neg_hi:[1,0]
	v_pk_mul_f32 v[100:101], v[100:101], v[114:115] op_sel_hi:[1,0]
	v_pk_fma_f32 v[26:27], v[26:27], v[58:59], v[100:101]
	s_waitcnt lgkmcnt(8)
	v_pk_add_f32 v[102:103], v[60:61], 1.0 op_sel_hi:[1,0] neg_lo:[1,0] neg_hi:[1,0]
	v_pk_mul_f32 v[102:103], v[102:103], v[114:115] op_sel_hi:[1,0]
	v_pk_fma_f32 v[28:29], v[28:29], v[60:61], v[102:103]
	v_pk_add_f32 v[104:105], v[62:63], 1.0 op_sel_hi:[1,0] neg_lo:[1,0] neg_hi:[1,0]
	v_pk_mul_f32 v[104:105], v[104:105], v[114:115] op_sel_hi:[1,0]
	v_pk_fma_f32 v[30:31], v[30:31], v[62:63], v[104:105]
	s_waitcnt lgkmcnt(0)
	v_fma_f32 v128, v66, v0, 0
	v_fmac_f32_e32 v128, v67, v1
	v_fmac_f32_e32 v128, v68, v2
	v_fmac_f32_e32 v128, v69, v3
	v_fmac_f32_e32 v128, v70, v4
	v_fmac_f32_e32 v128, v71, v5
	v_fmac_f32_e32 v128, v72, v6
	v_fmac_f32_e32 v128, v73, v7
	v_fmac_f32_e32 v128, v74, v8
	v_fmac_f32_e32 v128, v75, v9
	v_fmac_f32_e32 v128, v76, v10
	v_fmac_f32_e32 v128, v77, v11
	v_fmac_f32_e32 v128, v78, v12
	v_fmac_f32_e32 v128, v79, v13
	v_fmac_f32_e32 v128, v80, v14
	v_fmac_f32_e32 v128, v81, v15
	v_fmac_f32_e32 v128, v82, v16
	v_fmac_f32_e32 v128, v83, v17
	v_fmac_f32_e32 v128, v84, v18
	v_fmac_f32_e32 v128, v85, v19
	v_fmac_f32_e32 v128, v86, v20
	v_fmac_f32_e32 v128, v87, v21
	v_fmac_f32_e32 v128, v88, v22
	v_fmac_f32_e32 v128, v89, v23
	v_fmac_f32_e32 v128, v90, v24
	v_fmac_f32_e32 v128, v91, v25
	v_fmac_f32_e32 v128, v92, v26
	v_fmac_f32_e32 v128, v93, v27
	v_fmac_f32_e32 v128, v94, v28
	v_fmac_f32_e32 v128, v95, v29
	v_fmac_f32_e32 v128, v96, v30
	v_fmac_f32_e32 v128, v97, v31
	ds_write_b32 v127, v128 offset:8192
	ds_read_b128 v[32:35], v126 offset:2560
	ds_read_b128 v[36:39], v126 offset:2576
	ds_read_b128 v[40:43], v126 offset:2592
	ds_read_b128 v[44:47], v126 offset:2608
	ds_read_b128 v[48:51], v126 offset:2624
	ds_read_b128 v[52:55], v126 offset:2640
	ds_read_b128 v[56:59], v126 offset:2656
	ds_read_b128 v[60:63], v126 offset:2672
	ds_read_b128 v[66:69], v126 offset:6656
	ds_read_b128 v[70:73], v126 offset:6672
	ds_read_b128 v[74:77], v126 offset:6688
	ds_read_b128 v[78:81], v126 offset:6704
	s_waitcnt lgkmcnt(11)
	v_pk_add_f32 v[98:99], v[32:33], 1.0 op_sel_hi:[1,0] neg_lo:[1,0] neg_hi:[1,0]
	v_pk_mul_f32 v[98:99], v[98:99], v[116:117] op_sel_hi:[1,0]
	v_pk_fma_f32 v[0:1], v[0:1], v[32:33], v[98:99]
	v_pk_add_f32 v[100:101], v[34:35], 1.0 op_sel_hi:[1,0] neg_lo:[1,0] neg_hi:[1,0]
	v_pk_mul_f32 v[100:101], v[100:101], v[116:117] op_sel_hi:[1,0]
	v_pk_fma_f32 v[2:3], v[2:3], v[34:35], v[100:101]
	s_waitcnt lgkmcnt(10)
	v_pk_add_f32 v[102:103], v[36:37], 1.0 op_sel_hi:[1,0] neg_lo:[1,0] neg_hi:[1,0]
	v_pk_mul_f32 v[102:103], v[102:103], v[116:117] op_sel_hi:[1,0]
	v_pk_fma_f32 v[4:5], v[4:5], v[36:37], v[102:103]
	v_pk_add_f32 v[104:105], v[38:39], 1.0 op_sel_hi:[1,0] neg_lo:[1,0] neg_hi:[1,0]
	v_pk_mul_f32 v[104:105], v[104:105], v[116:117] op_sel_hi:[1,0]
	v_pk_fma_f32 v[6:7], v[6:7], v[38:39], v[104:105]
	s_waitcnt lgkmcnt(9)
	v_pk_add_f32 v[98:99], v[40:41], 1.0 op_sel_hi:[1,0] neg_lo:[1,0] neg_hi:[1,0]
	v_pk_mul_f32 v[98:99], v[98:99], v[116:117] op_sel_hi:[1,0]
	v_pk_fma_f32 v[8:9], v[8:9], v[40:41], v[98:99]
	v_pk_add_f32 v[100:101], v[42:43], 1.0 op_sel_hi:[1,0] neg_lo:[1,0] neg_hi:[1,0]
	v_pk_mul_f32 v[100:101], v[100:101], v[116:117] op_sel_hi:[1,0]
	v_pk_fma_f32 v[10:11], v[10:11], v[42:43], v[100:101]
	s_waitcnt lgkmcnt(8)
	v_pk_add_f32 v[102:103], v[44:45], 1.0 op_sel_hi:[1,0] neg_lo:[1,0] neg_hi:[1,0]
	v_pk_mul_f32 v[102:103], v[102:103], v[116:117] op_sel_hi:[1,0]
	v_pk_fma_f32 v[12:13], v[12:13], v[44:45], v[102:103]
	v_pk_add_f32 v[104:105], v[46:47], 1.0 op_sel_hi:[1,0] neg_lo:[1,0] neg_hi:[1,0]
	v_pk_mul_f32 v[104:105], v[104:105], v[116:117] op_sel_hi:[1,0]
	v_pk_fma_f32 v[14:15], v[14:15], v[46:47], v[104:105]
	ds_read_b128 v[82:85], v126 offset:6720
	ds_read_b128 v[86:89], v126 offset:6736
	ds_read_b128 v[90:93], v126 offset:6752
	ds_read_b128 v[94:97], v126 offset:6768
	s_waitcnt lgkmcnt(11)
	v_pk_add_f32 v[98:99], v[48:49], 1.0 op_sel_hi:[1,0] neg_lo:[1,0] neg_hi:[1,0]
	v_pk_mul_f32 v[98:99], v[98:99], v[116:117] op_sel_hi:[1,0]
	v_pk_fma_f32 v[16:17], v[16:17], v[48:49], v[98:99]
	v_pk_add_f32 v[100:101], v[50:51], 1.0 op_sel_hi:[1,0] neg_lo:[1,0] neg_hi:[1,0]
	v_pk_mul_f32 v[100:101], v[100:101], v[116:117] op_sel_hi:[1,0]
	v_pk_fma_f32 v[18:19], v[18:19], v[50:51], v[100:101]
	s_waitcnt lgkmcnt(10)
	v_pk_add_f32 v[102:103], v[52:53], 1.0 op_sel_hi:[1,0] neg_lo:[1,0] neg_hi:[1,0]
	v_pk_mul_f32 v[102:103], v[102:103], v[116:117] op_sel_hi:[1,0]
	v_pk_fma_f32 v[20:21], v[20:21], v[52:53], v[102:103]
	v_pk_add_f32 v[104:105], v[54:55], 1.0 op_sel_hi:[1,0] neg_lo:[1,0] neg_hi:[1,0]
	v_pk_mul_f32 v[104:105], v[104:105], v[116:117] op_sel_hi:[1,0]
	v_pk_fma_f32 v[22:23], v[22:23], v[54:55], v[104:105]
	s_waitcnt lgkmcnt(9)
	v_pk_add_f32 v[98:99], v[56:57], 1.0 op_sel_hi:[1,0] neg_lo:[1,0] neg_hi:[1,0]
	v_pk_mul_f32 v[98:99], v[98:99], v[116:117] op_sel_hi:[1,0]
	v_pk_fma_f32 v[24:25], v[24:25], v[56:57], v[98:99]
	v_pk_add_f32 v[100:101], v[58:59], 1.0 op_sel_hi:[1,0] neg_lo:[1,0] neg_hi:[1,0]
	v_pk_mul_f32 v[100:101], v[100:101], v[116:117] op_sel_hi:[1,0]
	v_pk_fma_f32 v[26:27], v[26:27], v[58:59], v[100:101]
	s_waitcnt lgkmcnt(8)
	v_pk_add_f32 v[102:103], v[60:61], 1.0 op_sel_hi:[1,0] neg_lo:[1,0] neg_hi:[1,0]
	v_pk_mul_f32 v[102:103], v[102:103], v[116:117] op_sel_hi:[1,0]
	v_pk_fma_f32 v[28:29], v[28:29], v[60:61], v[102:103]
	v_pk_add_f32 v[104:105], v[62:63], 1.0 op_sel_hi:[1,0] neg_lo:[1,0] neg_hi:[1,0]
	v_pk_mul_f32 v[104:105], v[104:105], v[116:117] op_sel_hi:[1,0]
	v_pk_fma_f32 v[30:31], v[30:31], v[62:63], v[104:105]
	s_waitcnt lgkmcnt(0)
	v_fma_f32 v128, v66, v0, 0
	v_fmac_f32_e32 v128, v67, v1
	v_fmac_f32_e32 v128, v68, v2
	v_fmac_f32_e32 v128, v69, v3
	v_fmac_f32_e32 v128, v70, v4
	v_fmac_f32_e32 v128, v71, v5
	v_fmac_f32_e32 v128, v72, v6
	v_fmac_f32_e32 v128, v73, v7
	v_fmac_f32_e32 v128, v74, v8
	v_fmac_f32_e32 v128, v75, v9
	v_fmac_f32_e32 v128, v76, v10
	v_fmac_f32_e32 v128, v77, v11
	v_fmac_f32_e32 v128, v78, v12
	v_fmac_f32_e32 v128, v79, v13
	v_fmac_f32_e32 v128, v80, v14
	v_fmac_f32_e32 v128, v81, v15
	v_fmac_f32_e32 v128, v82, v16
	v_fmac_f32_e32 v128, v83, v17
	v_fmac_f32_e32 v128, v84, v18
	v_fmac_f32_e32 v128, v85, v19
	v_fmac_f32_e32 v128, v86, v20
	v_fmac_f32_e32 v128, v87, v21
	v_fmac_f32_e32 v128, v88, v22
	v_fmac_f32_e32 v128, v89, v23
	v_fmac_f32_e32 v128, v90, v24
	v_fmac_f32_e32 v128, v91, v25
	v_fmac_f32_e32 v128, v92, v26
	v_fmac_f32_e32 v128, v93, v27
	v_fmac_f32_e32 v128, v94, v28
	v_fmac_f32_e32 v128, v95, v29
	v_fmac_f32_e32 v128, v96, v30
	v_fmac_f32_e32 v128, v97, v31
	ds_write_b32 v127, v128 offset:10240
	ds_read_b128 v[32:35], v126 offset:3072
	ds_read_b128 v[36:39], v126 offset:3088
	ds_read_b128 v[40:43], v126 offset:3104
	ds_read_b128 v[44:47], v126 offset:3120
	ds_read_b128 v[48:51], v126 offset:3136
	ds_read_b128 v[52:55], v126 offset:3152
	ds_read_b128 v[56:59], v126 offset:3168
	ds_read_b128 v[60:63], v126 offset:3184
	ds_read_b128 v[66:69], v126 offset:7168
	ds_read_b128 v[70:73], v126 offset:7184
	ds_read_b128 v[74:77], v126 offset:7200
	ds_read_b128 v[78:81], v126 offset:7216
	s_waitcnt lgkmcnt(11)
	v_pk_add_f32 v[98:99], v[32:33], 1.0 op_sel_hi:[1,0] neg_lo:[1,0] neg_hi:[1,0]
	v_pk_mul_f32 v[98:99], v[98:99], v[118:119] op_sel_hi:[1,0]
	v_pk_fma_f32 v[0:1], v[0:1], v[32:33], v[98:99]
	v_pk_add_f32 v[100:101], v[34:35], 1.0 op_sel_hi:[1,0] neg_lo:[1,0] neg_hi:[1,0]
	v_pk_mul_f32 v[100:101], v[100:101], v[118:119] op_sel_hi:[1,0]
	v_pk_fma_f32 v[2:3], v[2:3], v[34:35], v[100:101]
	s_waitcnt lgkmcnt(10)
	v_pk_add_f32 v[102:103], v[36:37], 1.0 op_sel_hi:[1,0] neg_lo:[1,0] neg_hi:[1,0]
	v_pk_mul_f32 v[102:103], v[102:103], v[118:119] op_sel_hi:[1,0]
	v_pk_fma_f32 v[4:5], v[4:5], v[36:37], v[102:103]
	v_pk_add_f32 v[104:105], v[38:39], 1.0 op_sel_hi:[1,0] neg_lo:[1,0] neg_hi:[1,0]
	v_pk_mul_f32 v[104:105], v[104:105], v[118:119] op_sel_hi:[1,0]
	v_pk_fma_f32 v[6:7], v[6:7], v[38:39], v[104:105]
	s_waitcnt lgkmcnt(9)
	v_pk_add_f32 v[98:99], v[40:41], 1.0 op_sel_hi:[1,0] neg_lo:[1,0] neg_hi:[1,0]
	v_pk_mul_f32 v[98:99], v[98:99], v[118:119] op_sel_hi:[1,0]
	v_pk_fma_f32 v[8:9], v[8:9], v[40:41], v[98:99]
	v_pk_add_f32 v[100:101], v[42:43], 1.0 op_sel_hi:[1,0] neg_lo:[1,0] neg_hi:[1,0]
	v_pk_mul_f32 v[100:101], v[100:101], v[118:119] op_sel_hi:[1,0]
	v_pk_fma_f32 v[10:11], v[10:11], v[42:43], v[100:101]
	s_waitcnt lgkmcnt(8)
	v_pk_add_f32 v[102:103], v[44:45], 1.0 op_sel_hi:[1,0] neg_lo:[1,0] neg_hi:[1,0]
	v_pk_mul_f32 v[102:103], v[102:103], v[118:119] op_sel_hi:[1,0]
	v_pk_fma_f32 v[12:13], v[12:13], v[44:45], v[102:103]
	v_pk_add_f32 v[104:105], v[46:47], 1.0 op_sel_hi:[1,0] neg_lo:[1,0] neg_hi:[1,0]
	v_pk_mul_f32 v[104:105], v[104:105], v[118:119] op_sel_hi:[1,0]
	v_pk_fma_f32 v[14:15], v[14:15], v[46:47], v[104:105]
	ds_read_b128 v[82:85], v126 offset:7232
	ds_read_b128 v[86:89], v126 offset:7248
	ds_read_b128 v[90:93], v126 offset:7264
	ds_read_b128 v[94:97], v126 offset:7280
	s_waitcnt lgkmcnt(11)
	v_pk_add_f32 v[98:99], v[48:49], 1.0 op_sel_hi:[1,0] neg_lo:[1,0] neg_hi:[1,0]
	v_pk_mul_f32 v[98:99], v[98:99], v[118:119] op_sel_hi:[1,0]
	v_pk_fma_f32 v[16:17], v[16:17], v[48:49], v[98:99]
	v_pk_add_f32 v[100:101], v[50:51], 1.0 op_sel_hi:[1,0] neg_lo:[1,0] neg_hi:[1,0]
	v_pk_mul_f32 v[100:101], v[100:101], v[118:119] op_sel_hi:[1,0]
	v_pk_fma_f32 v[18:19], v[18:19], v[50:51], v[100:101]
	s_waitcnt lgkmcnt(10)
	v_pk_add_f32 v[102:103], v[52:53], 1.0 op_sel_hi:[1,0] neg_lo:[1,0] neg_hi:[1,0]
	v_pk_mul_f32 v[102:103], v[102:103], v[118:119] op_sel_hi:[1,0]
	v_pk_fma_f32 v[20:21], v[20:21], v[52:53], v[102:103]
	v_pk_add_f32 v[104:105], v[54:55], 1.0 op_sel_hi:[1,0] neg_lo:[1,0] neg_hi:[1,0]
	v_pk_mul_f32 v[104:105], v[104:105], v[118:119] op_sel_hi:[1,0]
	v_pk_fma_f32 v[22:23], v[22:23], v[54:55], v[104:105]
	s_waitcnt lgkmcnt(9)
	v_pk_add_f32 v[98:99], v[56:57], 1.0 op_sel_hi:[1,0] neg_lo:[1,0] neg_hi:[1,0]
	v_pk_mul_f32 v[98:99], v[98:99], v[118:119] op_sel_hi:[1,0]
	v_pk_fma_f32 v[24:25], v[24:25], v[56:57], v[98:99]
	v_pk_add_f32 v[100:101], v[58:59], 1.0 op_sel_hi:[1,0] neg_lo:[1,0] neg_hi:[1,0]
	v_pk_mul_f32 v[100:101], v[100:101], v[118:119] op_sel_hi:[1,0]
	v_pk_fma_f32 v[26:27], v[26:27], v[58:59], v[100:101]
	s_waitcnt lgkmcnt(8)
	v_pk_add_f32 v[102:103], v[60:61], 1.0 op_sel_hi:[1,0] neg_lo:[1,0] neg_hi:[1,0]
	v_pk_mul_f32 v[102:103], v[102:103], v[118:119] op_sel_hi:[1,0]
	v_pk_fma_f32 v[28:29], v[28:29], v[60:61], v[102:103]
	v_pk_add_f32 v[104:105], v[62:63], 1.0 op_sel_hi:[1,0] neg_lo:[1,0] neg_hi:[1,0]
	v_pk_mul_f32 v[104:105], v[104:105], v[118:119] op_sel_hi:[1,0]
	v_pk_fma_f32 v[30:31], v[30:31], v[62:63], v[104:105]
	s_waitcnt lgkmcnt(0)
	v_fma_f32 v128, v66, v0, 0
	v_fmac_f32_e32 v128, v67, v1
	v_fmac_f32_e32 v128, v68, v2
	v_fmac_f32_e32 v128, v69, v3
	v_fmac_f32_e32 v128, v70, v4
	v_fmac_f32_e32 v128, v71, v5
	v_fmac_f32_e32 v128, v72, v6
	v_fmac_f32_e32 v128, v73, v7
	v_fmac_f32_e32 v128, v74, v8
	v_fmac_f32_e32 v128, v75, v9
	v_fmac_f32_e32 v128, v76, v10
	v_fmac_f32_e32 v128, v77, v11
	v_fmac_f32_e32 v128, v78, v12
	v_fmac_f32_e32 v128, v79, v13
	v_fmac_f32_e32 v128, v80, v14
	v_fmac_f32_e32 v128, v81, v15
	v_fmac_f32_e32 v128, v82, v16
	v_fmac_f32_e32 v128, v83, v17
	v_fmac_f32_e32 v128, v84, v18
	v_fmac_f32_e32 v128, v85, v19
	v_fmac_f32_e32 v128, v86, v20
	v_fmac_f32_e32 v128, v87, v21
	v_fmac_f32_e32 v128, v88, v22
	v_fmac_f32_e32 v128, v89, v23
	v_fmac_f32_e32 v128, v90, v24
	v_fmac_f32_e32 v128, v91, v25
	v_fmac_f32_e32 v128, v92, v26
	v_fmac_f32_e32 v128, v93, v27
	v_fmac_f32_e32 v128, v94, v28
	v_fmac_f32_e32 v128, v95, v29
	v_fmac_f32_e32 v128, v96, v30
	v_fmac_f32_e32 v128, v97, v31
	ds_write_b32 v127, v128 offset:12288
	ds_read_b128 v[32:35], v126 offset:3584
	ds_read_b128 v[36:39], v126 offset:3600
	ds_read_b128 v[40:43], v126 offset:3616
	ds_read_b128 v[44:47], v126 offset:3632
	ds_read_b128 v[48:51], v126 offset:3648
	ds_read_b128 v[52:55], v126 offset:3664
	ds_read_b128 v[56:59], v126 offset:3680
	ds_read_b128 v[60:63], v126 offset:3696
	ds_read_b128 v[66:69], v126 offset:7680
	ds_read_b128 v[70:73], v126 offset:7696
	ds_read_b128 v[74:77], v126 offset:7712
	ds_read_b128 v[78:81], v126 offset:7728
	s_waitcnt lgkmcnt(11)
	v_pk_add_f32 v[98:99], v[32:33], 1.0 op_sel_hi:[1,0] neg_lo:[1,0] neg_hi:[1,0]
	v_pk_mul_f32 v[98:99], v[98:99], v[120:121] op_sel_hi:[1,0]
	v_pk_fma_f32 v[0:1], v[0:1], v[32:33], v[98:99]
	v_pk_add_f32 v[100:101], v[34:35], 1.0 op_sel_hi:[1,0] neg_lo:[1,0] neg_hi:[1,0]
	v_pk_mul_f32 v[100:101], v[100:101], v[120:121] op_sel_hi:[1,0]
	v_pk_fma_f32 v[2:3], v[2:3], v[34:35], v[100:101]
	s_waitcnt lgkmcnt(10)
	v_pk_add_f32 v[102:103], v[36:37], 1.0 op_sel_hi:[1,0] neg_lo:[1,0] neg_hi:[1,0]
	v_pk_mul_f32 v[102:103], v[102:103], v[120:121] op_sel_hi:[1,0]
	v_pk_fma_f32 v[4:5], v[4:5], v[36:37], v[102:103]
	v_pk_add_f32 v[104:105], v[38:39], 1.0 op_sel_hi:[1,0] neg_lo:[1,0] neg_hi:[1,0]
	v_pk_mul_f32 v[104:105], v[104:105], v[120:121] op_sel_hi:[1,0]
	v_pk_fma_f32 v[6:7], v[6:7], v[38:39], v[104:105]
	s_waitcnt lgkmcnt(9)
	v_pk_add_f32 v[98:99], v[40:41], 1.0 op_sel_hi:[1,0] neg_lo:[1,0] neg_hi:[1,0]
	v_pk_mul_f32 v[98:99], v[98:99], v[120:121] op_sel_hi:[1,0]
	v_pk_fma_f32 v[8:9], v[8:9], v[40:41], v[98:99]
	v_pk_add_f32 v[100:101], v[42:43], 1.0 op_sel_hi:[1,0] neg_lo:[1,0] neg_hi:[1,0]
	v_pk_mul_f32 v[100:101], v[100:101], v[120:121] op_sel_hi:[1,0]
	v_pk_fma_f32 v[10:11], v[10:11], v[42:43], v[100:101]
	s_waitcnt lgkmcnt(8)
	v_pk_add_f32 v[102:103], v[44:45], 1.0 op_sel_hi:[1,0] neg_lo:[1,0] neg_hi:[1,0]
	v_pk_mul_f32 v[102:103], v[102:103], v[120:121] op_sel_hi:[1,0]
	v_pk_fma_f32 v[12:13], v[12:13], v[44:45], v[102:103]
	v_pk_add_f32 v[104:105], v[46:47], 1.0 op_sel_hi:[1,0] neg_lo:[1,0] neg_hi:[1,0]
	v_pk_mul_f32 v[104:105], v[104:105], v[120:121] op_sel_hi:[1,0]
	v_pk_fma_f32 v[14:15], v[14:15], v[46:47], v[104:105]
	ds_read_b128 v[82:85], v126 offset:7744
	ds_read_b128 v[86:89], v126 offset:7760
	ds_read_b128 v[90:93], v126 offset:7776
	ds_read_b128 v[94:97], v126 offset:7792
	s_waitcnt lgkmcnt(11)
	v_pk_add_f32 v[98:99], v[48:49], 1.0 op_sel_hi:[1,0] neg_lo:[1,0] neg_hi:[1,0]
	v_pk_mul_f32 v[98:99], v[98:99], v[120:121] op_sel_hi:[1,0]
	v_pk_fma_f32 v[16:17], v[16:17], v[48:49], v[98:99]
	v_pk_add_f32 v[100:101], v[50:51], 1.0 op_sel_hi:[1,0] neg_lo:[1,0] neg_hi:[1,0]
	v_pk_mul_f32 v[100:101], v[100:101], v[120:121] op_sel_hi:[1,0]
	v_pk_fma_f32 v[18:19], v[18:19], v[50:51], v[100:101]
	s_waitcnt lgkmcnt(10)
	v_pk_add_f32 v[102:103], v[52:53], 1.0 op_sel_hi:[1,0] neg_lo:[1,0] neg_hi:[1,0]
	v_pk_mul_f32 v[102:103], v[102:103], v[120:121] op_sel_hi:[1,0]
	v_pk_fma_f32 v[20:21], v[20:21], v[52:53], v[102:103]
	v_pk_add_f32 v[104:105], v[54:55], 1.0 op_sel_hi:[1,0] neg_lo:[1,0] neg_hi:[1,0]
	v_pk_mul_f32 v[104:105], v[104:105], v[120:121] op_sel_hi:[1,0]
	v_pk_fma_f32 v[22:23], v[22:23], v[54:55], v[104:105]
	s_waitcnt lgkmcnt(9)
	v_pk_add_f32 v[98:99], v[56:57], 1.0 op_sel_hi:[1,0] neg_lo:[1,0] neg_hi:[1,0]
	v_pk_mul_f32 v[98:99], v[98:99], v[120:121] op_sel_hi:[1,0]
	v_pk_fma_f32 v[24:25], v[24:25], v[56:57], v[98:99]
	v_pk_add_f32 v[100:101], v[58:59], 1.0 op_sel_hi:[1,0] neg_lo:[1,0] neg_hi:[1,0]
	v_pk_mul_f32 v[100:101], v[100:101], v[120:121] op_sel_hi:[1,0]
	v_pk_fma_f32 v[26:27], v[26:27], v[58:59], v[100:101]
	s_waitcnt lgkmcnt(8)
	v_pk_add_f32 v[102:103], v[60:61], 1.0 op_sel_hi:[1,0] neg_lo:[1,0] neg_hi:[1,0]
	v_pk_mul_f32 v[102:103], v[102:103], v[120:121] op_sel_hi:[1,0]
	v_pk_fma_f32 v[28:29], v[28:29], v[60:61], v[102:103]
	v_pk_add_f32 v[104:105], v[62:63], 1.0 op_sel_hi:[1,0] neg_lo:[1,0] neg_hi:[1,0]
	v_pk_mul_f32 v[104:105], v[104:105], v[120:121] op_sel_hi:[1,0]
	v_pk_fma_f32 v[30:31], v[30:31], v[62:63], v[104:105]
	s_waitcnt lgkmcnt(0)
	v_fma_f32 v128, v66, v0, 0
	v_fmac_f32_e32 v128, v67, v1
	v_fmac_f32_e32 v128, v68, v2
	v_fmac_f32_e32 v128, v69, v3
	v_fmac_f32_e32 v128, v70, v4
	v_fmac_f32_e32 v128, v71, v5
	v_fmac_f32_e32 v128, v72, v6
	v_fmac_f32_e32 v128, v73, v7
	v_fmac_f32_e32 v128, v74, v8
	v_fmac_f32_e32 v128, v75, v9
	v_fmac_f32_e32 v128, v76, v10
	v_fmac_f32_e32 v128, v77, v11
	v_fmac_f32_e32 v128, v78, v12
	v_fmac_f32_e32 v128, v79, v13
	v_fmac_f32_e32 v128, v80, v14
	v_fmac_f32_e32 v128, v81, v15
	v_fmac_f32_e32 v128, v82, v16
	v_fmac_f32_e32 v128, v83, v17
	v_fmac_f32_e32 v128, v84, v18
	v_fmac_f32_e32 v128, v85, v19
	v_fmac_f32_e32 v128, v86, v20
	v_fmac_f32_e32 v128, v87, v21
	v_fmac_f32_e32 v128, v88, v22
	v_fmac_f32_e32 v128, v89, v23
	v_fmac_f32_e32 v128, v90, v24
	v_fmac_f32_e32 v128, v91, v25
	v_fmac_f32_e32 v128, v92, v26
	v_fmac_f32_e32 v128, v93, v27
	v_fmac_f32_e32 v128, v94, v28
	v_fmac_f32_e32 v128, v95, v29
	v_fmac_f32_e32 v128, v96, v30
	v_fmac_f32_e32 v128, v97, v31
	ds_write_b32 v127, v128 offset:14336
	s_add_u32 s16, s88, 0x8600000
	s_addc_u32 s17, s89, 0
	s_add_u32 s16, s16, s14
	s_addc_u32 s17, s17, 0
	global_store_dword v123, v0, s[16:17]
	global_store_dword v123, v1, s[16:17] offset:512
	global_store_dword v123, v2, s[16:17] offset:1024
	global_store_dword v123, v3, s[16:17] offset:1536
	global_store_dword v123, v4, s[16:17] offset:2048
	global_store_dword v123, v5, s[16:17] offset:2560
	global_store_dword v123, v6, s[16:17] offset:3072
	global_store_dword v123, v7, s[16:17] offset:3584
	s_add_u32 s16, s16, 0x1000
	s_addc_u32 s17, s17, 0
	global_store_dword v123, v8, s[16:17]
	global_store_dword v123, v9, s[16:17] offset:512
	global_store_dword v123, v10, s[16:17] offset:1024
	global_store_dword v123, v11, s[16:17] offset:1536
	global_store_dword v123, v12, s[16:17] offset:2048
	global_store_dword v123, v13, s[16:17] offset:2560
	global_store_dword v123, v14, s[16:17] offset:3072
	global_store_dword v123, v15, s[16:17] offset:3584
	s_add_u32 s16, s16, 0x1000
	s_addc_u32 s17, s17, 0
	global_store_dword v123, v16, s[16:17]
	global_store_dword v123, v17, s[16:17] offset:512
	global_store_dword v123, v18, s[16:17] offset:1024
	global_store_dword v123, v19, s[16:17] offset:1536
	global_store_dword v123, v20, s[16:17] offset:2048
	global_store_dword v123, v21, s[16:17] offset:2560
	global_store_dword v123, v22, s[16:17] offset:3072
	global_store_dword v123, v23, s[16:17] offset:3584
	s_add_u32 s16, s16, 0x1000
	s_addc_u32 s17, s17, 0
	global_store_dword v123, v24, s[16:17]
	global_store_dword v123, v25, s[16:17] offset:512
	global_store_dword v123, v26, s[16:17] offset:1024
	global_store_dword v123, v27, s[16:17] offset:1536
	global_store_dword v123, v28, s[16:17] offset:2048
	global_store_dword v123, v29, s[16:17] offset:2560
	global_store_dword v123, v30, s[16:17] offset:3072
	global_store_dword v123, v31, s[16:17] offset:3584
	s_waitcnt lgkmcnt(0)
	s_barrier
	v_lshrrev_b32_e32 v98, 7, v64
	v_lshlrev_b32_e32 v99, 11, v98
	v_lshl_add_u32 v99, v129, 2, v99
	v_add_u32_e32 v99, 0x2000, v99
	ds_read_b32 v100, v99
	ds_read_b32 v101, v99 offset:512
	ds_read_b32 v102, v99 offset:1024
	ds_read_b32 v103, v99 offset:1536
	ds_read_b32 v104, v99 offset:8192
	ds_read_b32 v122, v99 offset:8704
	ds_read_b32 v124, v99 offset:9216
	ds_read_b32 v125, v99 offset:9728
	s_lshl_b32 s2, s6, 12
	s_lshl_b32 s3, s8, 9
	s_add_u32 s2, s2, s3
	v_lshlrev_b32_e32 v126, 12, v98
	v_lshl_add_u32 v126, v129, 2, v126
	v_add_u32_e32 v126, s2, v126
	s_add_u32 s10, s90, 0xf12b600
	s_addc_u32 s11, s91, 0
	s_waitcnt lgkmcnt(4)
	v_add_f32_e32 v100, v100, v101
	v_add_f32_e32 v100, v100, v102
	v_add_f32_e32 v100, v100, v103
	global_store_dword v126, v100, s[10:11]
	s_waitcnt lgkmcnt(0)
	v_add_f32_e32 v104, v104, v122
	v_add_f32_e32 v104, v104, v124
	v_add_f32_e32 v104, v104, v125
	v_add_u32_e32 v126, 0x4000, v126
	global_store_dword v126, v104, s[10:11]
	s_mov_b64 s[0:1], exec

.LBB0_939:
	s_lshl_b32 s0, s23, 8
	s_or_b32 s0, s0, s24
	s_or_b32 s9, s0, s22
	s_and_b64 s[0:1], s[10:11], exec
	s_cselect_b32 s0, s20, 0x264f1600
	s_add_u32 s0, s90, s0
	s_addc_u32 s1, s91, 0
	s_lshl_b32 s9, s9, 13
	s_add_u32 s0, s0, s9
	s_addc_u32 s1, s1, 0
	s_and_b64 s[10:11], s[10:11], exec
	s_cselect_b32 s10, s21, 0x268f1600
	s_add_u32 s10, s90, s10
	s_addc_u32 s11, s91, 0
	s_add_u32 s10, s10, s9
	s_addc_u32 s11, s11, 0
	s_lshl_b32 s4, s4, 11
	s_add_u32 s4, s6, s4
	s_addc_u32 s7, s7, 0
	s_add_u32 s6, s4, s8
	s_addc_u32 s7, s7, 0
	v_mov_b32_e32 v35, v11
	v_lshl_add_u64 v[0:1], s[6:7], 0, v[34:35]
	v_mov_b32_e32 v37, v11
	v_lshl_add_u64 v[0:1], v[0:1], 0, v[36:37]
	v_lshl_add_u64 v[2:3], v[0:1], 0, v[16:17]
	v_lshl_add_u64 v[38:39], v[0:1], 0, v[22:23]
	v_lshl_add_u64 v[48:49], v[0:1], 0, v[24:25]
	v_lshl_add_u64 v[50:51], v[0:1], 0, v[26:27]
	s_waitcnt lgkmcnt(0)
	s_barrier
	v_lshl_add_u64 v[4:5], v[0:1], 0, v[18:19]
	v_lshl_add_u64 v[6:7], v[0:1], 0, v[20:21]
	v_lshl_add_u64 v[52:53], v[0:1], 0, v[28:29]
	v_lshl_add_u64 v[0:1], v[0:1], 0, v[30:31]
	ds_read_b128 v[0:3], v46
	ds_read_b128 v[4:7], v46 offset:16
	s_add_i32 s12, s12, s33
	s_cmpk_lt_i32 s12, 0x400
	s_waitcnt lgkmcnt(1)
	v_cvt_pk_bf16_f32 v0, v0, v1
	v_cvt_pk_bf16_f32 v1, v2, v3
	s_waitcnt lgkmcnt(0)
	v_cvt_pk_bf16_f32 v2, v4, v5
	v_cvt_pk_bf16_f32 v3, v6, v7
	v_lshl_add_u64 v[4:5], s[0:1], 0, v[14:15]
	global_store_dwordx4 v[4:5], v[0:3], off
	v_lshl_add_u64 v[4:5], s[10:11], 0, v[32:33]
	s_waitcnt vmcnt(3)
	v_cvt_pk_bf16_f32 v0, v110, v111
	v_cvt_pk_bf16_f32 v1, v112, v113
	v_cvt_pk_bf16_f32 v2, v114, v115
	v_cvt_pk_bf16_f32 v3, v116, v117
	global_store_dwordx4 v[4:5], v[0:3], off
	s_barrier
	s_cbranch_scc0 .LBB0_942
.LBB0_940:
	s_bfe_u32 s23, s12, 0x10008
	s_and_b32 s22, s12, 0x80
	s_and_b32 s24, s12, 0x7f
	s_and_b32 s0, s12, 0xfffffe00
	s_cmpk_lg_i32 s0, 0x200
	s_cselect_b64 s[0:1], -1, 0
	s_cmpk_lt_u32 s24, 0x70
	s_cselect_b64 s[6:7], -1, 0
	s_or_b64 s[0:1], s[0:1], s[6:7]
	s_cmpk_lt_u32 s12, 0x200
	s_cselect_b64 s[10:11], -1, 0
	v_readlane_b32 s52, v239, 19
	s_and_b64 s[6:7], s[10:11], exec
	v_readlane_b32 s58, v239, 25
	v_readlane_b32 s59, v239, 26
	v_readlane_b32 s60, v239, 27
	v_readlane_b32 s61, v239, 28
	s_cselect_b32 s7, s14, s16
	s_cselect_b32 s6, s13, s15
	s_cselect_b32 s27, s59, s61
	s_cselect_b32 s26, s58, s60
	s_lshl_b32 s4, s23, 12
	s_lshl_b32 s25, s24, 5
	s_or_b32 s4, s4, s25
	v_lshl_add_u64 v[0:1], s[4:5], 0, v[8:9]
	v_lshlrev_b64 v[0:1], 11, v[0:1]
	v_lshl_add_u64 v[0:1], s[6:7], 0, v[0:1]
	s_lshl_b32 s8, s22, 2
	s_mov_b32 s9, s5
	v_lshl_add_u64 v[0:1], v[0:1], 0, s[8:9]
	v_lshl_add_u64 v[38:39], v[0:1], 0, v[10:11]
	global_load_dwordx4 v[0:3], v[38:39], off
	global_load_dwordx4 v[4:7], v[38:39], off offset:16
	global_load_dwordx4 v[48:51], v10, s[26:27]
	global_load_dwordx4 v[52:55], v10, s[26:27] offset:16
	s_lshl_b32 s28, s4, 11
	s_add_u32 s28, s6, s28
	s_addc_u32 s29, s7, 0
	s_add_u32 s28, s28, s8
	s_addc_u32 s29, s29, 0
	v_mov_b32_e32 v100, v34
	v_mov_b32_e32 v101, v11
	v_mov_b32_e32 v102, v36
	v_mov_b32_e32 v103, v11
	v_lshl_add_u64 v[100:101], s[28:29], 0, v[100:101]
	v_lshl_add_u64 v[100:101], v[100:101], 0, v[102:103]
	v_lshl_add_u64 v[102:103], v[100:101], 0, v[16:17]
	global_load_dword v110, v[102:103], off offset:1024
	v_lshl_add_u64 v[102:103], v[100:101], 0, v[18:19]
	global_load_dword v111, v[102:103], off offset:1024
	v_lshl_add_u64 v[102:103], v[100:101], 0, v[20:21]
	global_load_dword v112, v[102:103], off offset:1024
	v_lshl_add_u64 v[102:103], v[100:101], 0, v[22:23]
	global_load_dword v113, v[102:103], off offset:1024
	v_lshl_add_u64 v[102:103], v[100:101], 0, v[24:25]
	global_load_dword v114, v[102:103], off offset:1024
	v_lshl_add_u64 v[102:103], v[100:101], 0, v[26:27]
	global_load_dword v115, v[102:103], off offset:1024
	v_lshl_add_u64 v[102:103], v[100:101], 0, v[28:29]
	global_load_dword v116, v[102:103], off offset:1024
	v_lshl_add_u64 v[102:103], v[100:101], 0, v[30:31]
	global_load_dword v117, v[102:103], off offset:1024
	s_and_b64 vcc, exec, s[0:1]
	v_readlane_b32 s53, v239, 20
	v_readlane_b32 s54, v239, 21
	v_readlane_b32 s55, v239, 22
	v_readlane_b32 s56, v239, 23
	v_readlane_b32 s57, v239, 24
	v_readlane_b32 s62, v239, 29
	v_readlane_b32 s63, v239, 30
	v_readlane_b32 s64, v239, 31
	v_readlane_b32 s65, v239, 32
	v_readlane_b32 s66, v239, 33
	v_readlane_b32 s67, v239, 34
	s_waitcnt vmcnt(11)
	v_pk_mul_f32 v[56:57], v[2:3], v[2:3]
	v_pk_mul_f32 v[58:59], v[0:1], v[0:1]
	s_waitcnt vmcnt(10)
	v_pk_mul_f32 v[60:61], v[6:7], v[6:7]
	v_pk_mul_f32 v[62:63], v[4:5], v[4:5]
	v_pk_mov_b32 v[66:67], v[58:59], v[56:57] op_sel:[1,0]
	v_mov_b32_e32 v59, v57
	v_mov_b32_e32 v56, v60
	v_mov_b32_e32 v57, v62
	v_mov_b32_e32 v62, v61
	v_pk_add_f32 v[58:59], v[66:67], v[58:59]
	v_pk_add_f32 v[56:57], v[56:57], v[62:63]
	v_add_f32_e32 v35, v58, v59
	v_add_f32_e32 v35, v35, v57
	v_add_f32_e32 v35, v56, v35
	ds_bpermute_b32 v37, v40, v35
	s_waitcnt vmcnt(9)
	v_pk_mul_f32 v[2:3], v[2:3], v[50:51]
	v_pk_mul_f32 v[0:1], v[0:1], v[48:49]
	s_waitcnt vmcnt(8)
	v_pk_mul_f32 v[6:7], v[6:7], v[54:55]
	v_pk_mul_f32 v[4:5], v[4:5], v[52:53]
	s_waitcnt lgkmcnt(0)
	v_add_f32_e32 v35, v35, v37
	ds_bpermute_b32 v37, v41, v35
	s_waitcnt lgkmcnt(0)
	v_add_f32_e32 v35, v35, v37
	ds_bpermute_b32 v37, v42, v35
	s_waitcnt lgkmcnt(0)
	v_add_f32_e32 v35, v35, v37
	ds_bpermute_b32 v37, v43, v35
	s_waitcnt lgkmcnt(0)
	v_add_f32_e32 v35, v35, v37
	v_fmamk_f32 v35, v35, 0x3c000000, v45
	v_mul_f32_e32 v37, 0x4b800000, v35
	v_cmp_gt_f32_e64 s[0:1], s19, v35
	s_nop 1
	v_cndmask_b32_e64 v35, v35, v37, s[0:1]
	v_rsq_f32_e32 v35, v35
	s_nop 0
	v_mul_f32_e32 v37, 0x45800000, v35
	v_cndmask_b32_e64 v48, v35, v37, s[0:1]
	v_pk_mul_f32 v[2:3], v[2:3], v[48:49] op_sel_hi:[1,0]
	v_pk_mul_f32 v[0:1], v[0:1], v[48:49] op_sel_hi:[1,0]
	v_pk_mul_f32 v[6:7], v[6:7], v[48:49] op_sel_hi:[1,0]
	v_pk_mul_f32 v[4:5], v[4:5], v[48:49] op_sel_hi:[1,0]
	global_store_dwordx4 v[38:39], v[0:3], off
	global_store_dwordx4 v[38:39], v[4:7], off offset:16
	ds_write_b128 v44, v[0:3]
	ds_write_b128 v44, v[4:7] offset:16
	s_cbranch_vccnz .LBB0_939
	s_lshl_b32 s0, s23, 20
	s_add_u32 s26, s17, s0
	s_addc_u32 s27, s18, 0
	s_add_i32 s0, s25, 0xfffff200
	s_mov_b32 s1, s5
	s_lshl_b64 s[0:1], s[0:1], 11
	s_add_u32 s0, s26, s0
	s_addc_u32 s1, s27, s1
	v_lshl_add_u64 v[48:49], s[0:1], 0, v[12:13]
	v_lshl_add_u64 v[48:49], v[48:49], 0, s[8:9]
	v_lshl_add_u64 v[48:49], v[48:49], 0, v[10:11]
	global_store_dwordx4 v[48:49], v[0:3], off
	global_store_dwordx4 v[48:49], v[4:7], off offset:16
	global_load_dwordx4 v[0:3], v[38:39], off offset:1024
	s_nop 0
	global_load_dwordx4 v[4:7], v[38:39], off offset:1040
	s_waitcnt vmcnt(1)
	global_store_dwordx4 v[48:49], v[0:3], off offset:1024
	s_waitcnt vmcnt(1)
	global_store_dwordx4 v[48:49], v[4:7], off offset:1040
	s_branch .LBB0_939
